# GQA attention loop fast path: softmax-finish VALU interleaved into QK MFMA gaps, 2-deep K-frag prefetch, k-major PV with max tree in gaps
# speedup vs baseline: 1.0267x; 1.0054x over previous
; __device__ __forceinline__ void finishSM(f32x16& p0, f32x16& p1, float alpha, float& l_reg, bf16x8& pa0, bf16x8& pa1, bf16x8& pa2, bf16x8& pa3) {
; #pragma unroll
;   for (int r = 0; r < 16; ++r) p1[r] = __builtin_amdgcn_exp2f(p1[r]);
;   float ps = 0;
; #pragma unroll
;   for (int r = 0; r < 16; ++r) ps += p0[r];
; #pragma unroll
;   for (int r = 0; r < 16; ++r) ps += p1[r];
;   { auto rr = __builtin_amdgcn_permlane32_swap(__float_as_uint(ps), __float_as_uint(ps), false, false);
;     ps = __uint_as_float(rr[0]) + __uint_as_float(rr[1]); }
;   l_reg = l_reg * alpha + ps;
;     ...
;   PK4(p0, 0, pa0); PK4(p0, 8, pa1); PK4(p1, 0, pa2); PK4(p1, 8, pa3);
;     ...
; }
; template <int DQK> __device__ __forceinline__ void qkt(f32x16& p0, f32x16& p1, const char* Ks, const bf16x8* qr, int r32, int hi, const f32x16& negm) {
; #pragma unroll
;   for (int d0 = 0; d0 < DQK / 16; ++d0) { const int cb = (d0 * 16 + hi * 8) * 2;
;     const bf16x8 b0 = *reinterpret_cast<const bf16x8*>(Ks + (DQK == 128 ? KSWZ(r32, cb) : KSWZ64(r32, cb)));
;     const bf16x8 b1 = *reinterpret_cast<const bf16x8*>(Ks + (DQK == 128 ? KSWZ(32 + r32, cb) : KSWZ64(32 + r32, cb)));
;     if (d0 == 0) { p0 = __builtin_amdgcn_mfma_f32_32x32x16_bf16(b0, qr[0], negm, 0, 0, 0); p1 = __builtin_amdgcn_mfma_f32_32x32x16_bf16(b1, qr[0], negm, 0, 0, 0); }
;     else { p0 = __builtin_amdgcn_mfma_f32_32x32x16_bf16(b0, qr[d0], p0, 0, 0, 0); p1 = __builtin_amdgcn_mfma_f32_32x32x16_bf16(b1, qr[d0], p1, 0, 0, 0); } }
; }
.LBB0_69:
	s_add_i32 s99, s12, 64
	s_cmp_le_u32 s99, s16
	s_cbranch_scc0 .Lslow_g1
	ds_read_b128 v[198:201], v195 offset:57344
	ds_read_b128 v[202:205], v195 offset:49152
	ds_read_b128 v[244:247], v211 offset:57344
	ds_read_b128 v[206:209], v211 offset:49152
	v_add_f32_e32 v227, 0, v238
	v_add_f32_e32 v227, v240, v227
	v_cvt_pk_bf16_f32 v66, v238, v240
	v_add_f32_e32 v227, v236, v227
	v_add_f32_e32 v227, v239, v227
	v_cvt_pk_bf16_f32 v67, v236, v239
	v_add_f32_e32 v227, v235, v227
	v_add_f32_e32 v227, v237, v227
	v_cvt_pk_bf16_f32 v68, v235, v237
	v_add_f32_e32 v227, v233, v227
	v_add_f32_e32 v227, v234, v227
	v_cvt_pk_bf16_f32 v69, v233, v234
	s_waitcnt lgkmcnt(3)
	v_mfma_f32_32x32x16_bf16 v[114:129], v[198:201], v[174:177], v[82:97]
	v_add_f32_e32 v227, v184, v227
	v_add_f32_e32 v227, v232, v227
	v_cvt_pk_bf16_f32 v70, v184, v232
	v_add_f32_e32 v227, v183, v227
	v_add_f32_e32 v227, v185, v227
	s_waitcnt lgkmcnt(2)
	v_mfma_f32_32x32x16_bf16 v[130:145], v[202:205], v[174:177], v[82:97]
	ds_read_b128 v[198:201], v210 offset:57344
	ds_read_b128 v[202:205], v210 offset:49152
	v_cvt_pk_bf16_f32 v71, v183, v185
	v_add_f32_e32 v227, v180, v227
	v_add_f32_e32 v227, v182, v227
	v_cvt_pk_bf16_f32 v72, v180, v182
	v_add_f32_e32 v227, v179, v227
	s_waitcnt lgkmcnt(3)
	v_mfma_f32_32x32x16_bf16 v[114:129], v[244:247], v[170:173], v[114:129]
	v_add_f32_e32 v227, v181, v227
	v_cvt_pk_bf16_f32 v73, v179, v181
	v_exp_f32_e32 v98, v98
	v_exp_f32_e32 v99, v99
	v_permlane32_swap_b32_e32 v66, v68
	s_waitcnt lgkmcnt(2)
	v_mfma_f32_32x32x16_bf16 v[130:145], v[206:209], v[170:173], v[130:145]
	ds_read_b128 v[244:247], v197 offset:57344
	ds_read_b128 v[206:209], v197 offset:49152
	v_permlane32_swap_b32_e32 v67, v69
	v_permlane32_swap_b32_e32 v70, v72
	v_permlane32_swap_b32_e32 v71, v73
	v_exp_f32_e32 v100, v100
	v_add_f32_e32 v227, v98, v227
	s_waitcnt lgkmcnt(3)
	v_mfma_f32_32x32x16_bf16 v[114:129], v[198:201], v[166:169], v[114:129]
	v_exp_f32_e32 v101, v101
	v_add_f32_e32 v227, v99, v227
	v_exp_f32_e32 v102, v102
	v_add_f32_e32 v227, v100, v227
	v_exp_f32_e32 v103, v103
	s_waitcnt lgkmcnt(2)
	v_mfma_f32_32x32x16_bf16 v[130:145], v[202:205], v[166:169], v[130:145]
	ds_read_b128 v[198:201], v196 offset:57344
	ds_read_b128 v[202:205], v196 offset:49152
	v_add_f32_e32 v227, v101, v227
	v_exp_f32_e32 v104, v104
	v_add_f32_e32 v227, v102, v227
	v_exp_f32_e32 v105, v105
	s_waitcnt lgkmcnt(3)
	v_mfma_f32_32x32x16_bf16 v[114:129], v[244:247], v[162:165], v[114:129]
	v_add_f32_e32 v227, v103, v227
	v_exp_f32_e32 v106, v106
	v_add_f32_e32 v227, v104, v227
	v_exp_f32_e32 v107, v107
	s_waitcnt lgkmcnt(2)
	v_mfma_f32_32x32x16_bf16 v[130:145], v[206:209], v[162:165], v[130:145]
	ds_read_b128 v[244:247], v222 offset:57344
	ds_read_b128 v[206:209], v222 offset:49152
	v_add_f32_e32 v227, v105, v227
	v_exp_f32_e32 v108, v108
	v_add_f32_e32 v227, v106, v227
	v_exp_f32_e32 v109, v109
	s_waitcnt lgkmcnt(3)
	v_mfma_f32_32x32x16_bf16 v[114:129], v[198:201], v[158:161], v[114:129]
	v_add_f32_e32 v227, v107, v227
	v_exp_f32_e32 v110, v110
	v_add_f32_e32 v227, v108, v227
	v_exp_f32_e32 v111, v111
	s_waitcnt lgkmcnt(2)
	v_mfma_f32_32x32x16_bf16 v[130:145], v[202:205], v[158:161], v[130:145]
	ds_read_b128 v[198:201], v223 offset:57344
	ds_read_b128 v[202:205], v223 offset:49152
	v_add_f32_e32 v227, v109, v227
	v_exp_f32_e32 v112, v112
	v_add_f32_e32 v227, v110, v227
	v_exp_f32_e32 v113, v113
	s_waitcnt lgkmcnt(3)
	v_mfma_f32_32x32x16_bf16 v[114:129], v[244:247], v[154:157], v[114:129]
	v_add_f32_e32 v227, v111, v227
	v_add_f32_e32 v227, v112, v227
	v_add_f32_e32 v227, v113, v227
	v_mov_b32_e32 v228, v227
	s_waitcnt lgkmcnt(2)
	v_mfma_f32_32x32x16_bf16 v[130:145], v[206:209], v[154:157], v[130:145]
	ds_read_b128 v[244:247], v224 offset:57344
	ds_read_b128 v[206:209], v224 offset:49152
	v_cvt_pk_bf16_f32 v74, v98, v99
	v_cvt_pk_bf16_f32 v75, v100, v101
	v_cvt_pk_bf16_f32 v76, v102, v103
	v_cvt_pk_bf16_f32 v77, v104, v105
	s_waitcnt lgkmcnt(3)
	v_mfma_f32_32x32x16_bf16 v[114:129], v[198:201], v[150:153], v[114:129]
	v_cvt_pk_bf16_f32 v78, v106, v107
	v_cvt_pk_bf16_f32 v79, v108, v109
	v_cvt_pk_bf16_f32 v80, v110, v111
	v_cvt_pk_bf16_f32 v81, v112, v113
	s_waitcnt lgkmcnt(2)
; __device__ __forceinline__ void finishSM(f32x16& p0, f32x16& p1, float alpha, float& l_reg, bf16x8& pa0, bf16x8& pa1, bf16x8& pa2, bf16x8& pa3) {
; #pragma unroll
;   for (int r = 0; r < 16; ++r) p1[r] = __builtin_amdgcn_exp2f(p1[r]);
;   float ps = 0;
; #pragma unroll
;   for (int r = 0; r < 16; ++r) ps += p0[r];
; #pragma unroll
;   for (int r = 0; r < 16; ++r) ps += p1[r];
;   { auto rr = __builtin_amdgcn_permlane32_swap(__float_as_uint(ps), __float_as_uint(ps), false, false);
;     ps = __uint_as_float(rr[0]) + __uint_as_float(rr[1]); }
;   l_reg = l_reg * alpha + ps;
;     ...
;   PK4(p0, 0, pa0); PK4(p0, 8, pa1); PK4(p1, 0, pa2); PK4(p1, 8, pa3);
;     ...
; }
; template <int DQK> __device__ __forceinline__ void qkt(f32x16& p0, f32x16& p1, const char* Ks, const bf16x8* qr, int r32, int hi, const f32x16& negm) {
; #pragma unroll
;   for (int d0 = 0; d0 < DQK / 16; ++d0) { const int cb = (d0 * 16 + hi * 8) * 2;
;     const bf16x8 b0 = *reinterpret_cast<const bf16x8*>(Ks + (DQK == 128 ? KSWZ(r32, cb) : KSWZ64(r32, cb)));
;     const bf16x8 b1 = *reinterpret_cast<const bf16x8*>(Ks + (DQK == 128 ? KSWZ(32 + r32, cb) : KSWZ64(32 + r32, cb)));
;     if (d0 == 0) { p0 = __builtin_amdgcn_mfma_f32_32x32x16_bf16(b0, qr[0], negm, 0, 0, 0); p1 = __builtin_amdgcn_mfma_f32_32x32x16_bf16(b1, qr[0], negm, 0, 0, 0); }
;     else { p0 = __builtin_amdgcn_mfma_f32_32x32x16_bf16(b0, qr[d0], p0, 0, 0, 0); p1 = __builtin_amdgcn_mfma_f32_32x32x16_bf16(b1, qr[d0], p1, 0, 0, 0); } }
; }
; __device__ __forceinline__ int v_st(int k, int c) { const int kk = (k & ~0xC) | ((k & 4) << 1) | ((k & 8) >> 1); return ((kk >> 3) * 4 + (c >> 5)) * 512 + ((kk & 7) * 32 + (c & 31)) * 2; }
; __device__ __forceinline__ int v_rd_base(int lane) { return ((lane & 3) << 3) | (((lane >> 2) & 3) << 6) | (((lane >> 4) & 1) << 5) | (((lane >> 5) & 1) << 8); }
; template <int OFF> __device__ __forceinline__ s16x4 tr_read(int vb) {
;   s16x4 r; asm volatile("ds_read_b64_tr_b16 %0, %1 offset:%2" : "=&v"(r) : "v"(vb), "i"(OFF) : "memory"); return r;
; }
; template <int D0> __device__ __forceinline__ void pv_one(f32x16& od, int vb, bf16x8 pa0, bf16x8 pa1, bf16x8 pa2, bf16x8 pa3) {
;   const s16x4 l0 = tr_read<v_rd_off(D0, 0, 0)>(vb), h0 = tr_read<v_rd_off(D0, 0, 1)>(vb), l1 = tr_read<v_rd_off(D0, 1, 0)>(vb), h1 = tr_read<v_rd_off(D0, 1, 1)>(vb);
	v_mfma_f32_32x32x16_bf16 v[130:145], v[202:205], v[150:153], v[130:145]
	ds_read_b64_tr_b16 v[178:179], v193 offset:0
	ds_read_b64_tr_b16 v[180:181], v193 offset:0x800
	ds_read_b64_tr_b16 v[182:183], v193 offset:0x200
	ds_read_b64_tr_b16 v[184:185], v193 offset:0xa00
	ds_read_b64_tr_b16 v[198:199], v193 offset:0x400
	ds_read_b64_tr_b16 v[200:201], v193 offset:0xc00
	ds_read_b64_tr_b16 v[202:203], v193 offset:0x600
	ds_read_b64_tr_b16 v[204:205], v193 offset:0xe00
	v_permlane32_swap_b32_e32 v227, v228
	v_permlane32_swap_b32_e32 v74, v76
	v_permlane32_swap_b32_e32 v75, v77
	v_permlane32_swap_b32_e32 v78, v80
	s_waitcnt lgkmcnt(9)
	v_mfma_f32_32x32x16_bf16 v[114:129], v[244:247], v[146:149], v[114:129]
	v_permlane32_swap_b32_e32 v79, v81
	v_add_co_u32_e32 v218, vcc, s77, v186
	s_nop 1
	v_addc_co_u32_e32 v219, vcc, 0, v187, vcc
	s_waitcnt lgkmcnt(8)
	v_mfma_f32_32x32x16_bf16 v[130:145], v[206:209], v[146:149], v[130:145]
	global_load_dwordx4 v[98:101], v[186:187], off offset:512
	global_load_dwordx4 v[102:105], v[186:187], off
	global_load_dwordx4 v[110:113], v[218:219], off offset:512
	global_load_dwordx4 v[106:109], v[218:219], off
	s_waitcnt lgkmcnt(6)
	v_mfma_f32_32x32x16_bf16 v[2:17], v[66:69], v[178:181], v[2:17]
	ds_read_b64_tr_b16 v[178:179], v193 offset:0x1000
	ds_read_b64_tr_b16 v[180:181], v193 offset:0x1800
	s_waitcnt lgkmcnt(6)
	v_mfma_f32_32x32x16_bf16 v[50:65], v[66:69], v[182:185], v[50:65]
	ds_read_b64_tr_b16 v[182:183], v193 offset:0x1200
	ds_read_b64_tr_b16 v[184:185], v193 offset:0x1a00
	s_waitcnt lgkmcnt(6)
	v_mfma_f32_32x32x16_bf16 v[34:49], v[66:69], v[198:201], v[34:49]
	ds_read_b64_tr_b16 v[198:199], v193 offset:0x1400
	ds_read_b64_tr_b16 v[200:201], v193 offset:0x1c00
	s_waitcnt lgkmcnt(6)
	v_mfma_f32_32x32x16_bf16 v[18:33], v[66:69], v[202:205], v[18:33]
	ds_read_b64_tr_b16 v[202:203], v193 offset:0x1600
	ds_read_b64_tr_b16 v[204:205], v193 offset:0x1e00
	s_waitcnt lgkmcnt(6)
	v_mfma_f32_32x32x16_bf16 v[2:17], v[70:73], v[178:181], v[2:17]
	ds_read_b64_tr_b16 v[178:179], v193 offset:0x2000
	ds_read_b64_tr_b16 v[180:181], v193 offset:0x2800
	v_max_f32_e32 v218, v131, v131
	v_max_f32_e32 v219, v130, v130
	s_waitcnt lgkmcnt(6)
	v_mfma_f32_32x32x16_bf16 v[50:65], v[70:73], v[182:185], v[50:65]
	ds_read_b64_tr_b16 v[182:183], v193 offset:0x2200
	ds_read_b64_tr_b16 v[184:185], v193 offset:0x2a00
	v_max_f32_e32 v218, v219, v218
	v_max3_f32 v218, v218, v132, v133
	s_waitcnt lgkmcnt(6)
	v_mfma_f32_32x32x16_bf16 v[34:49], v[70:73], v[198:201], v[34:49]
	ds_read_b64_tr_b16 v[198:199], v193 offset:0x2400
	ds_read_b64_tr_b16 v[200:201], v193 offset:0x2c00
	v_max3_f32 v218, v218, v134, v135
	v_max3_f32 v218, v218, v136, v137
	s_waitcnt lgkmcnt(6)
	v_mfma_f32_32x32x16_bf16 v[18:33], v[70:73], v[202:205], v[18:33]
	ds_read_b64_tr_b16 v[202:203], v193 offset:0x2600
	ds_read_b64_tr_b16 v[204:205], v193 offset:0x2e00
	v_max3_f32 v218, v218, v138, v139
	v_max3_f32 v218, v218, v140, v141
	s_waitcnt lgkmcnt(6)
	v_mfma_f32_32x32x16_bf16 v[2:17], v[74:77], v[178:181], v[2:17]
	ds_read_b64_tr_b16 v[178:179], v193 offset:0x3000
	ds_read_b64_tr_b16 v[180:181], v193 offset:0x3800
	v_max3_f32 v218, v218, v142, v143
	v_max3_f32 v218, v218, v144, v145
	s_waitcnt lgkmcnt(6)
	v_mfma_f32_32x32x16_bf16 v[50:65], v[74:77], v[182:185], v[50:65]
	ds_read_b64_tr_b16 v[182:183], v193 offset:0x3200
	ds_read_b64_tr_b16 v[184:185], v193 offset:0x3a00
	v_max3_f32 v218, v218, v114, v115
	v_max3_f32 v218, v218, v116, v117
	s_waitcnt lgkmcnt(6)
	v_mfma_f32_32x32x16_bf16 v[34:49], v[74:77], v[198:201], v[34:49]
	ds_read_b64_tr_b16 v[198:199], v193 offset:0x3400
	ds_read_b64_tr_b16 v[200:201], v193 offset:0x3c00
	v_max3_f32 v218, v218, v118, v119
	v_max3_f32 v218, v218, v120, v121
	s_waitcnt lgkmcnt(6)
	v_mfma_f32_32x32x16_bf16 v[18:33], v[74:77], v[202:205], v[18:33]
	ds_read_b64_tr_b16 v[202:203], v193 offset:0x3600
	ds_read_b64_tr_b16 v[204:205], v193 offset:0x3e00
	v_max3_f32 v218, v218, v122, v123
	v_max3_f32 v218, v218, v124, v125
	s_waitcnt lgkmcnt(6)
	v_mfma_f32_32x32x16_bf16 v[2:17], v[78:81], v[178:181], v[2:17]
	v_max3_f32 v218, v218, v126, v127
	s_waitcnt lgkmcnt(4)
	v_mfma_f32_32x32x16_bf16 v[50:65], v[78:81], v[182:185], v[50:65]
	v_max3_f32 v218, v218, v128, v129
	s_waitcnt lgkmcnt(2)
	v_mfma_f32_32x32x16_bf16 v[34:49], v[78:81], v[198:201], v[34:49]
	v_mov_b32_e32 v219, v218
	s_waitcnt lgkmcnt(0)
	v_mfma_f32_32x32x16_bf16 v[18:33], v[78:81], v[202:205], v[18:33]
	v_permlane32_swap_b32_e32 v218, v219
	v_max_f32_e32 v219, v219, v219
	v_max_f32_e32 v218, v218, v218
	v_max_f32_e32 v66, v218, v219
	s_branch .Ljoin_g1

; template <bool FIRST> __device__ __forceinline__ void partialSM(f32x16& p0, f32x16& p1, float& m_reg, float& alpha, f32x16& negm, float c_cur) {
;     ...
;   alpha = 1.f;
;   if (FIRST || !__builtin_expect(__all(pmax <= THR2), 1)) {
;     const float d = FIRST ? pmax : fmaxf(pmax, 0.f); m_reg += d; if (!FIRST) alpha = __builtin_amdgcn_exp2f(-d);
.Ljoin_g1:
	v_cmp_ge_f32_e32 vcc, s30, v66
	s_cmp_eq_u64 vcc, exec
	s_cbranch_scc0 .LBB0_87
	v_mov_b64_e32 v[66:67], v[82:83]
	v_mov_b32_e32 v229, 1.0
	v_mov_b64_e32 v[68:69], v[84:85]
	v_mov_b64_e32 v[70:71], v[86:87]
	v_mov_b64_e32 v[72:73], v[88:89]
	v_mov_b64_e32 v[74:75], v[90:91]
	v_mov_b64_e32 v[76:77], v[92:93]
	v_mov_b64_e32 v[78:79], v[94:95]
	v_mov_b64_e32 v[80:81], v[96:97]

; #define SBAR() __builtin_amdgcn_sched_barrier(0)
; #define SWAIT() do { if (SDEPTH == 1) asm volatile("s_waitcnt vmcnt(0)" ::: "memory"); else if (DQK == 128) asm volatile("s_waitcnt vmcnt(4)" ::: "memory"); else asm volatile("s_waitcnt vmcnt(3)" ::: "memory"); } while (0)
; __device__ __forceinline__ void finishSM(f32x16& p0, f32x16& p1, float alpha, float& l_reg, bf16x8& pa0, bf16x8& pa1, bf16x8& pa2, bf16x8& pa3) {
; #pragma unroll
;   for (int r = 0; r < 16; ++r) p1[r] = __builtin_amdgcn_exp2f(p1[r]);
;   float ps = 0;
; #pragma unroll
;   for (int r = 0; r < 16; ++r) ps += p0[r];
; #pragma unroll
;   for (int r = 0; r < 16; ++r) ps += p1[r];
;   { auto rr = __builtin_amdgcn_permlane32_swap(__float_as_uint(ps), __float_as_uint(ps), false, false);
;     ps = __uint_as_float(rr[0]) + __uint_as_float(rr[1]); }
;   l_reg = l_reg * alpha + ps;
;     ...
;   PK4(p0, 0, pa0); PK4(p0, 8, pa1); PK4(p1, 0, pa2); PK4(p1, 8, pa3);
;     ...
; }
; template <int DQK> __device__ __forceinline__ void qkt(f32x16& p0, f32x16& p1, const char* Ks, const bf16x8* qr, int r32, int hi, const f32x16& negm) {
; #pragma unroll
;   for (int d0 = 0; d0 < DQK / 16; ++d0) { const int cb = (d0 * 16 + hi * 8) * 2;
;     const bf16x8 b0 = *reinterpret_cast<const bf16x8*>(Ks + (DQK == 128 ? KSWZ(r32, cb) : KSWZ64(r32, cb)));
;     const bf16x8 b1 = *reinterpret_cast<const bf16x8*>(Ks + (DQK == 128 ? KSWZ(32 + r32, cb) : KSWZ64(32 + r32, cb)));
;     if (d0 == 0) { p0 = __builtin_amdgcn_mfma_f32_32x32x16_bf16(b0, qr[0], negm, 0, 0, 0); p1 = __builtin_amdgcn_mfma_f32_32x32x16_bf16(b1, qr[0], negm, 0, 0, 0); }
;     else { p0 = __builtin_amdgcn_mfma_f32_32x32x16_bf16(b0, qr[d0], p0, 0, 0, 0); p1 = __builtin_amdgcn_mfma_f32_32x32x16_bf16(b1, qr[d0], p1, 0, 0, 0); } }
; }
; template <int DQK, bool BIAS, bool VIRT = false>
; __device__ __forceinline__ void attn_pass(const bf16_t* __restrict__ Qb, const bf16_t* __restrict__ Kh, const bf16_t* __restrict__ Vh, int L, int NT, int qw0, const float* lut, f32x16 (&o)[4], char* lds, int nact) {
;     ...
;     __syncthreads(); SWAIT(); SWRITE(0, SE);
;     RESC(alB); __syncthreads();
;     NEGM(j + 1); SBAR(); qkt<DQK>(pA0, pA1, K_lds, qr, r32, hi, negm);
;     finishSM(pB0, pB1, alB, l_reg, pa0, pa1, pa2, pa3); SBAR();
;     if (SDEPTH == 1 || j + 3 < NT) SLOAD(SE, (j + 1 + SDEPTH) * KVBLK); SBAR();
.LBB0_76:
	s_add_i32 s14, s12, 0x80
	v_exp_f32_e32 v178, v130
	v_exp_f32_e32 v205, v131
	v_exp_f32_e32 v179, v132
	v_exp_f32_e32 v204, v133
	v_exp_f32_e32 v180, v134
	v_exp_f32_e32 v203, v135
	v_exp_f32_e32 v181, v136
	v_exp_f32_e32 v202, v137
	v_exp_f32_e32 v182, v138
	v_exp_f32_e32 v201, v139
	v_exp_f32_e32 v183, v140
	v_exp_f32_e32 v200, v141
	v_exp_f32_e32 v184, v142
	v_exp_f32_e32 v199, v143
	v_exp_f32_e32 v185, v144
	v_exp_f32_e32 v198, v145
	s_waitcnt lgkmcnt(0)
	s_barrier
	s_cmp_le_u32 s14, s16
	s_cbranch_scc0 .Lslow_g2
	ds_read_b128 v[232:235], v195 offset:40960
	ds_read_b128 v[236:239], v195 offset:32768
	ds_read_b128 v[244:247], v211 offset:40960
	ds_read_b128 v[240:243], v211 offset:32768
	v_add_f32_e32 v230, 0, v178
	v_add_f32_e32 v230, v205, v230
	v_cvt_pk_bf16_f32 v178, v178, v205
	v_add_f32_e32 v230, v179, v230
	v_add_f32_e32 v230, v204, v230
	v_cvt_pk_bf16_f32 v179, v179, v204
	v_add_f32_e32 v230, v180, v230
	v_add_f32_e32 v230, v203, v230
	v_cvt_pk_bf16_f32 v180, v180, v203
	v_add_f32_e32 v230, v181, v230
	v_add_f32_e32 v230, v202, v230
	v_cvt_pk_bf16_f32 v181, v181, v202
	s_waitcnt lgkmcnt(3)
	v_mfma_f32_32x32x16_bf16 v[98:113], v[232:235], v[174:177], v[82:97]
	v_add_f32_e32 v230, v182, v230
	v_add_f32_e32 v230, v201, v230
	v_cvt_pk_bf16_f32 v182, v182, v201
	v_add_f32_e32 v230, v183, v230
	v_add_f32_e32 v230, v200, v230
	s_waitcnt lgkmcnt(2)
	v_mfma_f32_32x32x16_bf16 v[130:145], v[236:239], v[174:177], v[82:97]
	ds_read_b128 v[232:235], v210 offset:40960
	ds_read_b128 v[236:239], v210 offset:32768
	v_cvt_pk_bf16_f32 v183, v183, v200
	v_add_f32_e32 v230, v184, v230
	v_add_f32_e32 v230, v199, v230
	v_cvt_pk_bf16_f32 v184, v184, v199
	v_add_f32_e32 v230, v185, v230
	s_waitcnt lgkmcnt(3)
	v_mfma_f32_32x32x16_bf16 v[98:113], v[244:247], v[170:173], v[98:113]
	v_add_f32_e32 v230, v198, v230
	v_cvt_pk_bf16_f32 v185, v185, v198
	v_exp_f32_e32 v114, v114
	v_exp_f32_e32 v115, v115
	v_permlane32_swap_b32_e32 v178, v180
	s_waitcnt lgkmcnt(2)
	v_mfma_f32_32x32x16_bf16 v[130:145], v[240:243], v[170:173], v[130:145]
	ds_read_b128 v[244:247], v197 offset:40960
	ds_read_b128 v[240:243], v197 offset:32768
	v_permlane32_swap_b32_e32 v179, v181
	v_permlane32_swap_b32_e32 v182, v184
	v_permlane32_swap_b32_e32 v183, v185
	v_exp_f32_e32 v116, v116
	v_add_f32_e32 v230, v114, v230
	s_waitcnt lgkmcnt(3)
	v_mfma_f32_32x32x16_bf16 v[98:113], v[232:235], v[166:169], v[98:113]
	v_exp_f32_e32 v117, v117
	v_add_f32_e32 v230, v115, v230
	v_exp_f32_e32 v118, v118
	v_add_f32_e32 v230, v116, v230
	v_exp_f32_e32 v119, v119
	s_waitcnt lgkmcnt(2)
	v_mfma_f32_32x32x16_bf16 v[130:145], v[236:239], v[166:169], v[130:145]
	ds_read_b128 v[232:235], v196 offset:40960
	ds_read_b128 v[236:239], v196 offset:32768
	v_add_f32_e32 v230, v117, v230
	v_exp_f32_e32 v120, v120
	v_add_f32_e32 v230, v118, v230
	v_exp_f32_e32 v121, v121
	s_waitcnt lgkmcnt(3)
	v_mfma_f32_32x32x16_bf16 v[98:113], v[244:247], v[162:165], v[98:113]
	v_add_f32_e32 v230, v119, v230
	v_exp_f32_e32 v122, v122
	v_add_f32_e32 v230, v120, v230
	v_exp_f32_e32 v123, v123
	s_waitcnt lgkmcnt(2)
	v_mfma_f32_32x32x16_bf16 v[130:145], v[240:243], v[162:165], v[130:145]
	ds_read_b128 v[244:247], v222 offset:40960
	ds_read_b128 v[240:243], v222 offset:32768
	v_add_f32_e32 v230, v121, v230
	v_exp_f32_e32 v124, v124
	v_add_f32_e32 v230, v122, v230
	v_exp_f32_e32 v125, v125
	s_waitcnt lgkmcnt(3)
	v_mfma_f32_32x32x16_bf16 v[98:113], v[232:235], v[158:161], v[98:113]
	v_add_f32_e32 v230, v123, v230
	v_exp_f32_e32 v126, v126
	v_add_f32_e32 v230, v124, v230
	v_exp_f32_e32 v127, v127
	s_waitcnt lgkmcnt(2)
	v_mfma_f32_32x32x16_bf16 v[130:145], v[236:239], v[158:161], v[130:145]
	ds_read_b128 v[232:235], v223 offset:40960
	ds_read_b128 v[236:239], v223 offset:32768
	v_add_f32_e32 v230, v125, v230
	v_exp_f32_e32 v128, v128
	v_add_f32_e32 v230, v126, v230
	v_exp_f32_e32 v129, v129
	s_waitcnt lgkmcnt(3)
	v_mfma_f32_32x32x16_bf16 v[98:113], v[244:247], v[154:157], v[98:113]
	v_add_f32_e32 v230, v127, v230
	v_add_f32_e32 v230, v128, v230
	v_add_f32_e32 v230, v129, v230
	v_mov_b32_e32 v231, v230
	s_waitcnt lgkmcnt(2)
	v_mfma_f32_32x32x16_bf16 v[130:145], v[240:243], v[154:157], v[130:145]
	ds_read_b128 v[244:247], v224 offset:40960
	ds_read_b128 v[240:243], v224 offset:32768
	v_cvt_pk_bf16_f32 v198, v114, v115
	v_cvt_pk_bf16_f32 v199, v116, v117
	v_cvt_pk_bf16_f32 v200, v118, v119
	v_cvt_pk_bf16_f32 v201, v120, v121
	s_waitcnt lgkmcnt(3)
	v_mfma_f32_32x32x16_bf16 v[98:113], v[232:235], v[150:153], v[98:113]
	v_cvt_pk_bf16_f32 v202, v122, v123
	v_cvt_pk_bf16_f32 v203, v124, v125
	v_cvt_pk_bf16_f32 v204, v126, v127
	v_cvt_pk_bf16_f32 v205, v128, v129
	s_waitcnt lgkmcnt(2)
	v_mfma_f32_32x32x16_bf16 v[130:145], v[236:239], v[150:153], v[130:145]
	ds_read_b64_tr_b16 v[206:207], v190 offset:0
	ds_read_b64_tr_b16 v[208:209], v190 offset:0x800
	ds_read_b64_tr_b16 v[232:233], v190 offset:0x200
	ds_read_b64_tr_b16 v[234:235], v190 offset:0xa00
	ds_read_b64_tr_b16 v[236:237], v190 offset:0x400
	ds_read_b64_tr_b16 v[238:239], v190 offset:0xc00
	v_permlane32_swap_b32_e32 v230, v231
	v_permlane32_swap_b32_e32 v198, v200
	v_permlane32_swap_b32_e32 v199, v201
	v_permlane32_swap_b32_e32 v202, v204
	s_waitcnt lgkmcnt(7)
	v_mfma_f32_32x32x16_bf16 v[98:113], v[244:247], v[146:149], v[98:113]
	v_permlane32_swap_b32_e32 v203, v205
	v_add_co_u32_e32 v218, vcc, s80, v186
	s_nop 1
	v_addc_co_u32_e32 v219, vcc, 0, v187, vcc
	s_waitcnt lgkmcnt(6)
	v_mfma_f32_32x32x16_bf16 v[130:145], v[240:243], v[146:149], v[130:145]
	ds_read_b64_tr_b16 v[240:241], v190 offset:0x600
	ds_read_b64_tr_b16 v[242:243], v190 offset:0xe00
	global_load_dwordx4 v[114:117], v[218:219], off offset:512
	global_load_dwordx4 v[118:121], v[218:219], off
	s_waitcnt lgkmcnt(6)
; __device__ __forceinline__ void finishSM(f32x16& p0, f32x16& p1, float alpha, float& l_reg, bf16x8& pa0, bf16x8& pa1, bf16x8& pa2, bf16x8& pa3) {
; #pragma unroll
;   for (int r = 0; r < 16; ++r) p1[r] = __builtin_amdgcn_exp2f(p1[r]);
;   float ps = 0;
; #pragma unroll
;   for (int r = 0; r < 16; ++r) ps += p0[r];
; #pragma unroll
;   for (int r = 0; r < 16; ++r) ps += p1[r];
;   { auto rr = __builtin_amdgcn_permlane32_swap(__float_as_uint(ps), __float_as_uint(ps), false, false);
;     ps = __uint_as_float(rr[0]) + __uint_as_float(rr[1]); }
;   l_reg = l_reg * alpha + ps;
;     ...
;   PK4(p0, 0, pa0); PK4(p0, 8, pa1); PK4(p1, 0, pa2); PK4(p1, 8, pa3);
;     ...
; }
; template <int DQK> __device__ __forceinline__ void qkt(f32x16& p0, f32x16& p1, const char* Ks, const bf16x8* qr, int r32, int hi, const f32x16& negm) {
; #pragma unroll
;   for (int d0 = 0; d0 < DQK / 16; ++d0) { const int cb = (d0 * 16 + hi * 8) * 2;
;     const bf16x8 b0 = *reinterpret_cast<const bf16x8*>(Ks + (DQK == 128 ? KSWZ(r32, cb) : KSWZ64(r32, cb)));
;     const bf16x8 b1 = *reinterpret_cast<const bf16x8*>(Ks + (DQK == 128 ? KSWZ(32 + r32, cb) : KSWZ64(32 + r32, cb)));
;     if (d0 == 0) { p0 = __builtin_amdgcn_mfma_f32_32x32x16_bf16(b0, qr[0], negm, 0, 0, 0); p1 = __builtin_amdgcn_mfma_f32_32x32x16_bf16(b1, qr[0], negm, 0, 0, 0); }
;     else { p0 = __builtin_amdgcn_mfma_f32_32x32x16_bf16(b0, qr[d0], p0, 0, 0, 0); p1 = __builtin_amdgcn_mfma_f32_32x32x16_bf16(b1, qr[d0], p1, 0, 0, 0); } }
; }
; __device__ __forceinline__ int v_st(int k, int c) { const int kk = (k & ~0xC) | ((k & 4) << 1) | ((k & 8) >> 1); return ((kk >> 3) * 4 + (c >> 5)) * 512 + ((kk & 7) * 32 + (c & 31)) * 2; }
; __device__ __forceinline__ int v_rd_base(int lane) { return ((lane & 3) << 3) | (((lane >> 2) & 3) << 6) | (((lane >> 4) & 1) << 5) | (((lane >> 5) & 1) << 8); }
; template <int OFF> __device__ __forceinline__ s16x4 tr_read(int vb) {
;   s16x4 r; asm volatile("ds_read_b64_tr_b16 %0, %1 offset:%2" : "=&v"(r) : "v"(vb), "i"(OFF) : "memory"); return r;
; }
; template <int D0> __device__ __forceinline__ void pv_one(f32x16& od, int vb, bf16x8 pa0, bf16x8 pa1, bf16x8 pa2, bf16x8 pa3) {
;   const s16x4 l0 = tr_read<v_rd_off(D0, 0, 0)>(vb), h0 = tr_read<v_rd_off(D0, 0, 1)>(vb), l1 = tr_read<v_rd_off(D0, 1, 0)>(vb), h1 = tr_read<v_rd_off(D0, 1, 1)>(vb);
	v_mfma_f32_32x32x16_bf16 v[2:17], v[178:181], v[206:209], v[2:17]
	ds_read_b64_tr_b16 v[206:207], v190 offset:0x1000
	ds_read_b64_tr_b16 v[208:209], v190 offset:0x1800
	v_add_co_u32_e32 v218, vcc, s81, v186
	s_nop 1
	v_addc_co_u32_e32 v219, vcc, 0, v187, vcc
	global_load_dwordx4 v[126:129], v[218:219], off offset:512
	global_load_dwordx4 v[122:125], v[218:219], off
	s_waitcnt lgkmcnt(6)
	v_mfma_f32_32x32x16_bf16 v[50:65], v[178:181], v[232:235], v[50:65]
	ds_read_b64_tr_b16 v[232:233], v190 offset:0x1200
	ds_read_b64_tr_b16 v[234:235], v190 offset:0x1a00
	s_waitcnt lgkmcnt(6)
	v_mfma_f32_32x32x16_bf16 v[34:49], v[178:181], v[236:239], v[34:49]
	ds_read_b64_tr_b16 v[236:237], v190 offset:0x1400
	ds_read_b64_tr_b16 v[238:239], v190 offset:0x1c00
	s_waitcnt lgkmcnt(6)
	v_mfma_f32_32x32x16_bf16 v[18:33], v[178:181], v[240:243], v[18:33]
	ds_read_b64_tr_b16 v[240:241], v190 offset:0x1600
	ds_read_b64_tr_b16 v[242:243], v190 offset:0x1e00
	s_waitcnt lgkmcnt(6)
	v_mfma_f32_32x32x16_bf16 v[2:17], v[182:185], v[206:209], v[2:17]
	ds_read_b64_tr_b16 v[206:207], v190 offset:0x2000
	ds_read_b64_tr_b16 v[208:209], v190 offset:0x2800
	v_max_f32_e32 v218, v131, v131
	v_max_f32_e32 v219, v130, v130
	s_waitcnt lgkmcnt(6)
	v_mfma_f32_32x32x16_bf16 v[50:65], v[182:185], v[232:235], v[50:65]
	ds_read_b64_tr_b16 v[232:233], v190 offset:0x2200
	ds_read_b64_tr_b16 v[234:235], v190 offset:0x2a00
	v_max_f32_e32 v218, v219, v218
	v_max3_f32 v218, v218, v132, v133
	s_waitcnt lgkmcnt(6)
	v_mfma_f32_32x32x16_bf16 v[34:49], v[182:185], v[236:239], v[34:49]
	ds_read_b64_tr_b16 v[236:237], v190 offset:0x2400
	ds_read_b64_tr_b16 v[238:239], v190 offset:0x2c00
	v_max3_f32 v218, v218, v134, v135
	v_max3_f32 v218, v218, v136, v137
	s_waitcnt lgkmcnt(6)
	v_mfma_f32_32x32x16_bf16 v[18:33], v[182:185], v[240:243], v[18:33]
	ds_read_b64_tr_b16 v[240:241], v190 offset:0x2600
	ds_read_b64_tr_b16 v[242:243], v190 offset:0x2e00
	v_max3_f32 v218, v218, v138, v139
	v_max3_f32 v218, v218, v140, v141
	s_waitcnt lgkmcnt(6)
	v_mfma_f32_32x32x16_bf16 v[2:17], v[198:201], v[206:209], v[2:17]
	ds_read_b64_tr_b16 v[206:207], v190 offset:0x3000
	ds_read_b64_tr_b16 v[208:209], v190 offset:0x3800
	v_max3_f32 v218, v218, v142, v143
	v_max3_f32 v218, v218, v144, v145
	s_waitcnt lgkmcnt(6)
	v_mfma_f32_32x32x16_bf16 v[50:65], v[198:201], v[232:235], v[50:65]
	ds_read_b64_tr_b16 v[232:233], v190 offset:0x3200
	ds_read_b64_tr_b16 v[234:235], v190 offset:0x3a00
	v_max3_f32 v218, v218, v98, v99
	v_max3_f32 v218, v218, v100, v101
	s_waitcnt lgkmcnt(6)
	v_mfma_f32_32x32x16_bf16 v[34:49], v[198:201], v[236:239], v[34:49]
	ds_read_b64_tr_b16 v[236:237], v190 offset:0x3400
	ds_read_b64_tr_b16 v[238:239], v190 offset:0x3c00
	v_max3_f32 v218, v218, v102, v103
	v_max3_f32 v218, v218, v104, v105
	s_waitcnt lgkmcnt(6)
	v_mfma_f32_32x32x16_bf16 v[18:33], v[198:201], v[240:243], v[18:33]
	ds_read_b64_tr_b16 v[240:241], v190 offset:0x3600
	ds_read_b64_tr_b16 v[242:243], v190 offset:0x3e00
	v_max3_f32 v218, v218, v106, v107
	v_max3_f32 v218, v218, v108, v109
	s_waitcnt lgkmcnt(6)
	v_mfma_f32_32x32x16_bf16 v[2:17], v[202:205], v[206:209], v[2:17]
	v_max3_f32 v218, v218, v110, v111
	s_waitcnt lgkmcnt(4)
	v_mfma_f32_32x32x16_bf16 v[50:65], v[202:205], v[232:235], v[50:65]
	v_max3_f32 v218, v218, v112, v113
	s_waitcnt lgkmcnt(2)
	v_mfma_f32_32x32x16_bf16 v[34:49], v[202:205], v[236:239], v[34:49]
	v_mov_b32_e32 v219, v218
	s_waitcnt lgkmcnt(0)
	v_mfma_f32_32x32x16_bf16 v[18:33], v[202:205], v[240:243], v[18:33]
	v_permlane32_swap_b32_e32 v218, v219
	v_max_f32_e32 v219, v219, v219
	v_max_f32_e32 v218, v218, v218
	v_max_f32_e32 v179, v218, v219
	s_branch .Ljoin_g2
.Lslow_g2:
	ds_read_b128 v[206:209], v195 offset:40960
	ds_read_b128 v[98:101], v195 offset:32768
	v_exp_f32_e32 v114, v114
	v_exp_f32_e32 v115, v115
	v_exp_f32_e32 v116, v116
	v_exp_f32_e32 v117, v117
	s_waitcnt lgkmcnt(0)
	v_mfma_f32_32x32x16_bf16 v[130:145], v[98:101], v[174:177], v[66:81]
	v_exp_f32_e32 v118, v118
	v_exp_f32_e32 v119, v119
	v_exp_f32_e32 v120, v120
	v_exp_f32_e32 v121, v121
	v_exp_f32_e32 v122, v122
	v_exp_f32_e32 v123, v123
	v_exp_f32_e32 v124, v124
	v_mfma_f32_32x32x16_bf16 v[98:113], v[206:209], v[174:177], v[66:81]
	ds_read_b128 v[206:209], v211 offset:40960
	ds_read_b128 v[230:233], v211 offset:32768
	v_exp_f32_e32 v125, v125
	v_exp_f32_e32 v126, v126
	v_exp_f32_e32 v127, v127
	v_exp_f32_e32 v128, v128
	v_exp_f32_e32 v129, v129
	s_waitcnt lgkmcnt(1)
	v_mfma_f32_32x32x16_bf16 v[98:113], v[206:209], v[170:173], v[98:113]
	s_waitcnt lgkmcnt(0)
	v_mfma_f32_32x32x16_bf16 v[130:145], v[230:233], v[170:173], v[130:145]
	ds_read_b128 v[206:209], v210 offset:40960
	ds_read_b128 v[230:233], v210 offset:32768
	s_waitcnt lgkmcnt(1)
	v_mfma_f32_32x32x16_bf16 v[98:113], v[206:209], v[166:169], v[98:113]
	s_waitcnt lgkmcnt(0)
	v_mfma_f32_32x32x16_bf16 v[130:145], v[230:233], v[166:169], v[130:145]
	ds_read_b128 v[206:209], v197 offset:40960
	ds_read_b128 v[230:233], v197 offset:32768
	s_waitcnt lgkmcnt(1)
	v_mfma_f32_32x32x16_bf16 v[98:113], v[206:209], v[162:165], v[98:113]
	s_waitcnt lgkmcnt(0)
	v_mfma_f32_32x32x16_bf16 v[130:145], v[230:233], v[162:165], v[130:145]
	ds_read_b128 v[206:209], v196 offset:40960
	ds_read_b128 v[230:233], v196 offset:32768
	s_waitcnt lgkmcnt(1)
	v_mfma_f32_32x32x16_bf16 v[98:113], v[206:209], v[158:161], v[98:113]
	s_waitcnt lgkmcnt(0)
	v_mfma_f32_32x32x16_bf16 v[130:145], v[230:233], v[158:161], v[130:145]
	ds_read_b128 v[206:209], v222 offset:40960
	ds_read_b128 v[230:233], v222 offset:32768
	s_waitcnt lgkmcnt(1)
	v_mfma_f32_32x32x16_bf16 v[98:113], v[206:209], v[154:157], v[98:113]
	s_waitcnt lgkmcnt(0)
; __device__ __forceinline__ void finishSM(f32x16& p0, f32x16& p1, float alpha, float& l_reg, bf16x8& pa0, bf16x8& pa1, bf16x8& pa2, bf16x8& pa3) {
; #pragma unroll
;   for (int r = 0; r < 16; ++r) p1[r] = __builtin_amdgcn_exp2f(p1[r]);
;   float ps = 0;
; #pragma unroll
;   for (int r = 0; r < 16; ++r) ps += p0[r];
; #pragma unroll
;   for (int r = 0; r < 16; ++r) ps += p1[r];
;   { auto rr = __builtin_amdgcn_permlane32_swap(__float_as_uint(ps), __float_as_uint(ps), false, false);
;     ps = __uint_as_float(rr[0]) + __uint_as_float(rr[1]); }
;   l_reg = l_reg * alpha + ps;
;     ...
;   PK4(p0, 0, pa0); PK4(p0, 8, pa1); PK4(p1, 0, pa2); PK4(p1, 8, pa3);
;     ...
; }
; template <int DQK> __device__ __forceinline__ void qkt(f32x16& p0, f32x16& p1, const char* Ks, const bf16x8* qr, int r32, int hi, const f32x16& negm) {
; #pragma unroll
;   for (int d0 = 0; d0 < DQK / 16; ++d0) { const int cb = (d0 * 16 + hi * 8) * 2;
;     const bf16x8 b0 = *reinterpret_cast<const bf16x8*>(Ks + (DQK == 128 ? KSWZ(r32, cb) : KSWZ64(r32, cb)));
;     const bf16x8 b1 = *reinterpret_cast<const bf16x8*>(Ks + (DQK == 128 ? KSWZ(32 + r32, cb) : KSWZ64(32 + r32, cb)));
;     if (d0 == 0) { p0 = __builtin_amdgcn_mfma_f32_32x32x16_bf16(b0, qr[0], negm, 0, 0, 0); p1 = __builtin_amdgcn_mfma_f32_32x32x16_bf16(b1, qr[0], negm, 0, 0, 0); }
;     else { p0 = __builtin_amdgcn_mfma_f32_32x32x16_bf16(b0, qr[d0], p0, 0, 0, 0); p1 = __builtin_amdgcn_mfma_f32_32x32x16_bf16(b1, qr[d0], p1, 0, 0, 0); } }
; }
; __device__ __forceinline__ int v_st(int k, int c) { const int kk = (k & ~0xC) | ((k & 4) << 1) | ((k & 8) >> 1); return ((kk >> 3) * 4 + (c >> 5)) * 512 + ((kk & 7) * 32 + (c & 31)) * 2; }
; __device__ __forceinline__ int v_rd_base(int lane) { return ((lane & 3) << 3) | (((lane >> 2) & 3) << 6) | (((lane >> 4) & 1) << 5) | (((lane >> 5) & 1) << 8); }
; template <int OFF> __device__ __forceinline__ s16x4 tr_read(int vb) {
;   s16x4 r; asm volatile("ds_read_b64_tr_b16 %0, %1 offset:%2" : "=&v"(r) : "v"(vb), "i"(OFF) : "memory"); return r;
; }
; template <int D0> __device__ __forceinline__ void pv_one(f32x16& od, int vb, bf16x8 pa0, bf16x8 pa1, bf16x8 pa2, bf16x8 pa3) {
;   const s16x4 l0 = tr_read<v_rd_off(D0, 0, 0)>(vb), h0 = tr_read<v_rd_off(D0, 0, 1)>(vb), l1 = tr_read<v_rd_off(D0, 1, 0)>(vb), h1 = tr_read<v_rd_off(D0, 1, 1)>(vb);
	v_mfma_f32_32x32x16_bf16 v[130:145], v[230:233], v[154:157], v[130:145]
	ds_read_b128 v[206:209], v223 offset:40960
	ds_read_b128 v[230:233], v223 offset:32768
	s_waitcnt lgkmcnt(1)
	v_mfma_f32_32x32x16_bf16 v[98:113], v[206:209], v[150:153], v[98:113]
	s_waitcnt lgkmcnt(0)
	v_mfma_f32_32x32x16_bf16 v[130:145], v[230:233], v[150:153], v[130:145]
	ds_read_b128 v[206:209], v224 offset:40960
	ds_read_b128 v[230:233], v224 offset:32768
	s_waitcnt lgkmcnt(1)
	v_mfma_f32_32x32x16_bf16 v[98:113], v[206:209], v[146:149], v[98:113]
	v_add_f32_e32 v206, 0, v178
	v_add_f32_e32 v206, v205, v206
	v_add_f32_e32 v206, v179, v206
	v_add_f32_e32 v206, v204, v206
	v_add_f32_e32 v206, v180, v206
	v_add_f32_e32 v206, v203, v206
	v_add_f32_e32 v206, v181, v206
	v_add_f32_e32 v206, v202, v206
	v_add_f32_e32 v206, v182, v206
	v_add_f32_e32 v206, v201, v206
	v_add_f32_e32 v206, v183, v206
	v_add_f32_e32 v206, v200, v206
	v_add_f32_e32 v206, v184, v206
	v_add_f32_e32 v206, v199, v206
	v_add_f32_e32 v206, v185, v206
	v_add_f32_e32 v206, v198, v206
	v_add_f32_e32 v206, v114, v206
	v_add_f32_e32 v206, v115, v206
	v_add_f32_e32 v206, v116, v206
	v_add_f32_e32 v206, v117, v206
	v_add_f32_e32 v206, v118, v206
	v_add_f32_e32 v206, v119, v206
	v_add_f32_e32 v206, v120, v206
	v_add_f32_e32 v206, v121, v206
	v_add_f32_e32 v206, v122, v206
	v_add_f32_e32 v206, v123, v206
	s_waitcnt lgkmcnt(0)
	v_mfma_f32_32x32x16_bf16 v[130:145], v[230:233], v[146:149], v[130:145]
	v_add_f32_e32 v206, v124, v206
	v_add_f32_e32 v206, v125, v206
	v_add_f32_e32 v206, v126, v206
	v_add_f32_e32 v206, v127, v206
	v_add_f32_e32 v206, v128, v206
	v_add_f32_e32 v230, v129, v206
	v_mov_b32_e32 v231, v230
	s_nop 1
	v_permlane32_swap_b32_e32 v230, v231
	v_cvt_pk_bf16_f32 v178, v178, v205
	v_cvt_pk_bf16_f32 v179, v179, v204
	v_cvt_pk_bf16_f32 v180, v180, v203
	v_cvt_pk_bf16_f32 v181, v181, v202
	v_cvt_pk_bf16_f32 v182, v182, v201
	v_cvt_pk_bf16_f32 v183, v183, v200
	v_cvt_pk_bf16_f32 v184, v184, v199
	v_cvt_pk_bf16_f32 v185, v185, v198
	v_cvt_pk_bf16_f32 v198, v114, v115
	v_cvt_pk_bf16_f32 v199, v116, v117
	v_cvt_pk_bf16_f32 v200, v118, v119
	v_cvt_pk_bf16_f32 v201, v120, v121
	v_cvt_pk_bf16_f32 v202, v122, v123
	v_cvt_pk_bf16_f32 v203, v124, v125
	v_cvt_pk_bf16_f32 v204, v126, v127
	v_cvt_pk_bf16_f32 v205, v128, v129
	s_nop 0
	v_permlane32_swap_b32_e32 v178, v180
	v_permlane32_swap_b32_e32 v179, v181
	v_permlane32_swap_b32_e32 v182, v184
	v_permlane32_swap_b32_e32 v183, v185
	v_permlane32_swap_b32_e32 v198, v200
	v_permlane32_swap_b32_e32 v199, v201
	v_permlane32_swap_b32_e32 v202, v204
	v_permlane32_swap_b32_e32 v203, v205
	v_add_co_u32_e32 v118, vcc, s80, v186
	s_nop 1
	v_addc_co_u32_e32 v119, vcc, 0, v187, vcc
	v_add_co_u32_e32 v122, vcc, s81, v186
	s_nop 1
	v_addc_co_u32_e32 v123, vcc, 0, v187, vcc
	global_load_dwordx4 v[114:117], v[118:119], off offset:512
	s_nop 0
	global_load_dwordx4 v[118:121], v[118:119], off
	s_nop 0
	global_load_dwordx4 v[126:129], v[122:123], off offset:512
	s_nop 0
	global_load_dwordx4 v[122:125], v[122:123], off
	ds_read_b64_tr_b16 v[206:207], v190 offset:0
	ds_read_b64_tr_b16 v[208:209], v190 offset:0x800
	ds_read_b64_tr_b16 v[232:233], v190 offset:0x1000
	ds_read_b64_tr_b16 v[234:235], v190 offset:0x1800
	ds_read_b64_tr_b16 v[236:237], v190 offset:0x2000
	ds_read_b64_tr_b16 v[238:239], v190 offset:0x2800
	ds_read_b64_tr_b16 v[240:241], v190 offset:0x3000
	ds_read_b64_tr_b16 v[242:243], v190 offset:0x3800
	s_waitcnt lgkmcnt(0)
	s_nop 0
	v_mfma_f32_32x32x16_bf16 v[2:17], v[178:181], v[206:209], v[2:17]
	ds_read_b64_tr_b16 v[206:207], v190 offset:0x200
	ds_read_b64_tr_b16 v[208:209], v190 offset:0xa00
	v_mfma_f32_32x32x16_bf16 v[2:17], v[182:185], v[232:235], v[2:17]
	ds_read_b64_tr_b16 v[232:233], v190 offset:0x1200
	ds_read_b64_tr_b16 v[234:235], v190 offset:0x1a00
	v_mfma_f32_32x32x16_bf16 v[2:17], v[198:201], v[236:239], v[2:17]
	ds_read_b64_tr_b16 v[236:237], v190 offset:0x2200
	ds_read_b64_tr_b16 v[238:239], v190 offset:0x2a00
	v_mfma_f32_32x32x16_bf16 v[2:17], v[202:205], v[240:243], v[2:17]
	ds_read_b64_tr_b16 v[240:241], v190 offset:0x3200
	ds_read_b64_tr_b16 v[242:243], v190 offset:0x3a00
	s_waitcnt lgkmcnt(0)
	v_mfma_f32_32x32x16_bf16 v[50:65], v[178:181], v[206:209], v[50:65]
	ds_read_b64_tr_b16 v[206:207], v190 offset:0x400
	ds_read_b64_tr_b16 v[208:209], v190 offset:0xc00
	v_mfma_f32_32x32x16_bf16 v[50:65], v[182:185], v[232:235], v[50:65]
	ds_read_b64_tr_b16 v[232:233], v190 offset:0x1400
	ds_read_b64_tr_b16 v[234:235], v190 offset:0x1c00
	v_mfma_f32_32x32x16_bf16 v[50:65], v[198:201], v[236:239], v[50:65]
	ds_read_b64_tr_b16 v[236:237], v190 offset:0x2400
	ds_read_b64_tr_b16 v[238:239], v190 offset:0x2c00
	v_mfma_f32_32x32x16_bf16 v[50:65], v[202:205], v[240:243], v[50:65]
	ds_read_b64_tr_b16 v[240:241], v190 offset:0x3400
	ds_read_b64_tr_b16 v[242:243], v190 offset:0x3c00
	s_waitcnt lgkmcnt(0)
	v_mfma_f32_32x32x16_bf16 v[34:49], v[178:181], v[206:209], v[34:49]
	ds_read_b64_tr_b16 v[206:207], v190 offset:0x600
	ds_read_b64_tr_b16 v[208:209], v190 offset:0xe00
	v_mfma_f32_32x32x16_bf16 v[34:49], v[182:185], v[232:235], v[34:49]
	ds_read_b64_tr_b16 v[232:233], v190 offset:0x1600
	ds_read_b64_tr_b16 v[234:235], v190 offset:0x1e00
	v_mfma_f32_32x32x16_bf16 v[34:49], v[198:201], v[236:239], v[34:49]
	ds_read_b64_tr_b16 v[236:237], v190 offset:0x2600
	ds_read_b64_tr_b16 v[238:239], v190 offset:0x2e00
	v_mfma_f32_32x32x16_bf16 v[34:49], v[202:205], v[240:243], v[34:49]
	ds_read_b64_tr_b16 v[240:241], v190 offset:0x3600
	ds_read_b64_tr_b16 v[242:243], v190 offset:0x3e00
	s_waitcnt lgkmcnt(0)
	v_mfma_f32_32x32x16_bf16 v[18:33], v[178:181], v[206:209], v[18:33]
	s_cmp_le_u32 s14, s16
	v_mfma_f32_32x32x16_bf16 v[18:33], v[182:185], v[232:235], v[18:33]
	v_mfma_f32_32x32x16_bf16 v[18:33], v[198:201], v[236:239], v[18:33]
	v_mfma_f32_32x32x16_bf16 v[18:33], v[202:205], v[240:243], v[18:33]
	s_cbranch_scc0 .LBB0_88

; template <bool FIRST> __device__ __forceinline__ void partialSM(f32x16& p0, f32x16& p1, float& m_reg, float& alpha, f32x16& negm, float c_cur) {
;     ...
;   alpha = 1.f;
;   if (FIRST || !__builtin_expect(__all(pmax <= THR2), 1)) {
;     const float d = FIRST ? pmax : fmaxf(pmax, 0.f); m_reg += d; if (!FIRST) alpha = __builtin_amdgcn_exp2f(-d);
.Ljoin_g2:
	v_cmp_ge_f32_e32 vcc, s30, v179
	s_cmp_eq_u64 vcc, exec
	v_mov_b32_e32 v178, 1.0
	s_cbranch_scc0 .LBB0_91

; #define SBAR() __builtin_amdgcn_sched_barrier(0)
; #define SLOAD(i, k0) do { sr_[i].vs0 = GLD8(&Vh[(long)((k0) + sr) * LD + sc]); sr_[i].vs1 = GLD8(&Vh[(long)((k0) + 32 + sr) * LD + sc]); \
;     if (DQK == 128) { sr_[i].ks0 = GLD8(&Kh[(long)((k0) + sr) * LD + sc]); sr_[i].ks1 = GLD8(&Kh[(long)((k0) + 32 + sr) * LD + sc]); } \
;     else { sr_[i].ks0 = GLD8(&Kh[(long)((k0) + kr) * LD + kc]); } } while (0)
; template <int DQK> __device__ __forceinline__ void qkt(f32x16& p0, f32x16& p1, const char* Ks, const bf16x8* qr, int r32, int hi, const f32x16& negm) {
; #pragma unroll
;   for (int d0 = 0; d0 < DQK / 16; ++d0) { const int cb = (d0 * 16 + hi * 8) * 2;
;     const bf16x8 b0 = *reinterpret_cast<const bf16x8*>(Ks + (DQK == 128 ? KSWZ(r32, cb) : KSWZ64(r32, cb)));
;     const bf16x8 b1 = *reinterpret_cast<const bf16x8*>(Ks + (DQK == 128 ? KSWZ(32 + r32, cb) : KSWZ64(32 + r32, cb)));
;     if (d0 == 0) { p0 = __builtin_amdgcn_mfma_f32_32x32x16_bf16(b0, qr[0], negm, 0, 0, 0); p1 = __builtin_amdgcn_mfma_f32_32x32x16_bf16(b1, qr[0], negm, 0, 0, 0); }
;     else { p0 = __builtin_amdgcn_mfma_f32_32x32x16_bf16(b0, qr[d0], p0, 0, 0, 0); p1 = __builtin_amdgcn_mfma_f32_32x32x16_bf16(b1, qr[d0], p1, 0, 0, 0); } }
; }
; template <int DQK, bool BIAS, bool VIRT = false>
; __device__ __forceinline__ void attn_pass(const bf16_t* __restrict__ Qb, const bf16_t* __restrict__ Kh, const bf16_t* __restrict__ Vh, int L, int NT, int qw0, const float* lut, f32x16 (&o)[4], char* lds, int nact) {
;     ...
;   SLOAD(SE, 0); asm volatile("s_waitcnt vmcnt(0)" ::: "memory"); SWRITE(0, SE); __syncthreads();
;   qkt<DQK>(pA0, pA1, K_lds, qr, r32, hi, negm); fixup<BIAS, VIRT>(pA0, pA1, 0, L, qw0, r32, hi, lut); partialSM<true>(pA0, pA1, m_reg, alA, negm, c_cur);
;   SLOAD(SO, KVBLK); if (SDEPTH == 2) { if (2 < NT) SLOAD(SE, 2 * KVBLK); }
;   SWAIT(); SWRITE(1, SO); __syncthreads();
;   for (int j = 1; j + 1 < NT; j += 2) {
;     NEGM(j); SBAR(); qkt<DQK>(pB0, pB1, K_lds + SHM_K, qr, r32, hi, negm);
;     finishSM(pA0, pA1, alA, l_reg, pa0, pa1, pa2, pa3); SBAR();
;     SLOAD(SO, (j + SDEPTH) * KVBLK); SBAR();
;     pv_d0(o, vb0, pa0, pa1, pa2, pa3); fixup<BIAS, VIRT>(pB0, pB1, j, L, qw0, r32, hi, lut); partialSM<false>(pB0, pB1, m_reg, alB, negm, c_cur);
.LBB0_218:
	s_add_i32 s99, s19, 0xffffff61
	s_cmp_lt_u32 s99, 0xfffffea3
	s_cbranch_scc0 .Lold_h1
	s_cmp_le_u32 s18, s47
	s_cbranch_scc0 .Lold_h1
	ds_read_b128 v[180:183], v225 offset:53248
	ds_read_b128 v[116:119], v225 offset:49152
	ds_read_b128 v[184:187], v227 offset:53248
	ds_read_b128 v[68:71], v227 offset:49152
	ds_read_b128 v[72:75], v228 offset:53248
	ds_read_b128 v[206:209], v228 offset:49152
	v_add_f32_e32 v0, 0, v148
	v_add_f32_e32 v0, v178, v0
	v_add_f32_e32 v0, v146, v0
	v_add_f32_e32 v0, v149, v0
	v_add_f32_e32 v0, v144, v0
	v_add_f32_e32 v0, v147, v0
	v_add_f32_e32 v0, v143, v0
	v_add_f32_e32 v0, v145, v0
	v_add_f32_e32 v0, v137, v0
	v_add_f32_e32 v0, v139, v0
	v_add_f32_e32 v0, v136, v0
	v_add_f32_e32 v0, v138, v0
	v_add_f32_e32 v0, v135, v0
	v_add_f32_e32 v0, v142, v0
	v_add_f32_e32 v0, v140, v0
	v_add_f32_e32 v0, v141, v0
	v_cvt_pk_bf16_f32 v76, v148, v178
	v_cvt_pk_bf16_f32 v77, v146, v149
	v_cvt_pk_bf16_f32 v78, v144, v147
	v_cvt_pk_bf16_f32 v79, v143, v145
	v_cvt_pk_bf16_f32 v80, v137, v139
	v_cvt_pk_bf16_f32 v81, v136, v138
	v_cvt_pk_bf16_f32 v82, v135, v142
	v_cvt_pk_bf16_f32 v83, v140, v141
	s_waitcnt lgkmcnt(6)
	v_cmp_neq_f32_e32 vcc, v133, v66
	s_cbranch_vccnz .Lcupd_f1
.Lcret_f1:
	s_waitcnt lgkmcnt(4)
	v_mfma_f32_32x32x16_bf16 v[84:99], v[116:119], v[162:165], v[236:251]
	v_mfma_f32_32x32x16_bf16 v[116:131], v[180:183], v[162:165], v[236:251]
	ds_read_b128 v[180:183], v226 offset:53248
	v_permlane32_swap_b32_e32 v76, v78
	v_permlane32_swap_b32_e32 v77, v79
	v_permlane32_swap_b32_e32 v80, v82
	v_permlane32_swap_b32_e32 v81, v83
	v_lshl_add_u64 v[148:149], v[194:195], 0, s[0:1]
	v_lshl_add_u64 v[196:197], v[192:193], 0, s[0:1]
	s_mov_b32 s4, 0x102b1000
	v_add_co_u32_e64 v132, s[4:5], s4, v148
	s_waitcnt lgkmcnt(3)
	v_mfma_f32_32x32x16_bf16 v[116:131], v[184:187], v[158:161], v[116:131]
	v_addc_co_u32_e64 v133, s[4:5], 0, v149, s[4:5]
	s_mov_b32 s4, 0x102f9000
	v_add_co_u32_e64 v202, s[4:5], s4, v148
	v_mfma_f32_32x32x16_bf16 v[84:99], v[68:71], v[158:161], v[84:99]
	ds_read_b128 v[184:187], v226 offset:49152
	v_addc_co_u32_e64 v203, s[4:5], 0, v149, s[4:5]
	s_mov_b32 s4, 0x102b0000
	v_add_co_u32_e64 v204, s[4:5], s4, v196
	s_waitcnt lgkmcnt(2)
	v_mfma_f32_32x32x16_bf16 v[116:131], v[72:75], v[154:157], v[116:131]
	v_addc_co_u32_e64 v205, s[4:5], 0, v197, s[4:5]
	v_mfma_f32_32x32x16_bf16 v[84:99], v[206:209], v[154:157], v[84:99]
	ds_read_b64_tr_b16 v[134:135], v223 offset:0
	ds_read_b64_tr_b16 v[136:137], v223 offset:0x800
	ds_read_b64_tr_b16 v[138:139], v223 offset:0x200
	ds_read_b64_tr_b16 v[140:141], v223 offset:0xa00
	ds_read_b64_tr_b16 v[142:143], v223 offset:0x400
	ds_read_b64_tr_b16 v[144:145], v223 offset:0xc00
	ds_read_b64_tr_b16 v[198:199], v223 offset:0x600
	ds_read_b64_tr_b16 v[200:201], v223 offset:0xe00
	s_waitcnt lgkmcnt(8)
	v_mfma_f32_32x32x16_bf16 v[116:131], v[180:183], v[150:153], v[116:131]
	v_mfma_f32_32x32x16_bf16 v[84:99], v[184:187], v[150:153], v[84:99]
	global_load_dwordx4 v[178:181], v[132:133], off
	global_load_dwordx4 v[182:185], v[202:203], off
	global_load_dwordx4 v[186:189], v[204:205], off offset:2048
	s_waitcnt lgkmcnt(6)
	v_mfma_f32_32x32x16_bf16 v[50:65], v[76:79], v[134:137], v[50:65]
	ds_read_b64_tr_b16 v[134:135], v223 offset:0x1000
	ds_read_b64_tr_b16 v[136:137], v223 offset:0x1800
	v_exp_f32_e32 v68, v100
	v_exp_f32_e32 v69, v101
	v_add_f32_e32 v0, v68, v0
	s_waitcnt lgkmcnt(6)
	v_mfma_f32_32x32x16_bf16 v[34:49], v[76:79], v[138:141], v[34:49]
	ds_read_b64_tr_b16 v[138:139], v223 offset:0x1200
	ds_read_b64_tr_b16 v[140:141], v223 offset:0x1a00
	v_exp_f32_e32 v70, v102
	v_add_f32_e32 v0, v69, v0
	v_exp_f32_e32 v71, v103
	v_add_f32_e32 v0, v70, v0
	s_waitcnt lgkmcnt(6)
	v_mfma_f32_32x32x16_bf16 v[18:33], v[76:79], v[142:145], v[18:33]
	ds_read_b64_tr_b16 v[142:143], v223 offset:0x1400
	ds_read_b64_tr_b16 v[144:145], v223 offset:0x1c00
	v_exp_f32_e32 v72, v104
	v_add_f32_e32 v0, v71, v0
	v_exp_f32_e32 v73, v105
	v_add_f32_e32 v0, v72, v0
	s_waitcnt lgkmcnt(6)
	v_mfma_f32_32x32x16_bf16 v[2:17], v[76:79], v[198:201], v[2:17]
	ds_read_b64_tr_b16 v[198:199], v223 offset:0x1600
	ds_read_b64_tr_b16 v[200:201], v223 offset:0x1e00
	v_exp_f32_e32 v74, v106
	v_add_f32_e32 v0, v73, v0
	v_exp_f32_e32 v75, v107
	v_add_f32_e32 v0, v74, v0
	v_add_f32_e32 v0, v75, v0
	s_waitcnt lgkmcnt(6)
; #define SBAR() __builtin_amdgcn_sched_barrier(0)
; template <int D0> __device__ __forceinline__ void pv_one(f32x16& od, int vb, bf16x8 pa0, bf16x8 pa1, bf16x8 pa2, bf16x8 pa3) {
;   const s16x4 l0 = tr_read<v_rd_off(D0, 0, 0)>(vb), h0 = tr_read<v_rd_off(D0, 0, 1)>(vb), l1 = tr_read<v_rd_off(D0, 1, 0)>(vb), h1 = tr_read<v_rd_off(D0, 1, 1)>(vb);
;   const s16x4 l2 = tr_read<v_rd_off(D0, 2, 0)>(vb), h2 = tr_read<v_rd_off(D0, 2, 1)>(vb), l3 = tr_read<v_rd_off(D0, 3, 0)>(vb), h3 = tr_read<v_rd_off(D0, 3, 1)>(vb);
;   asm volatile("s_waitcnt lgkmcnt(0)" ::: "memory"); SBAR();
;     ...
;   od = __builtin_amdgcn_mfma_f32_32x32x16_bf16(pa0, PK(l0, h0), od, 0, 0, 0);
;   od = __builtin_amdgcn_mfma_f32_32x32x16_bf16(pa1, PK(l1, h1), od, 0, 0, 0);
;   od = __builtin_amdgcn_mfma_f32_32x32x16_bf16(pa2, PK(l2, h2), od, 0, 0, 0);
;   od = __builtin_amdgcn_mfma_f32_32x32x16_bf16(pa3, PK(l3, h3), od, 0, 0, 0);
;     ...
; }
; __device__ __forceinline__ void pv_d0(f32x16* o, int vb, bf16x8 pa0, bf16x8 pa1, bf16x8 pa2, bf16x8 pa3) {
;   pv_one<0>(o[0], vb, pa0, pa1, pa2, pa3); pv_one<1>(o[1], vb, pa0, pa1, pa2, pa3); pv_one<2>(o[2], vb, pa0, pa1, pa2, pa3); pv_one<3>(o[3], vb, pa0, pa1, pa2, pa3);
	v_mfma_f32_32x32x16_bf16 v[50:65], v[80:83], v[134:137], v[50:65]
	ds_read_b64_tr_b16 v[134:135], v223 offset:0x2000
	ds_read_b64_tr_b16 v[136:137], v223 offset:0x2800
	v_cvt_pk_bf16_f32 v100, v68, v69
	v_cvt_pk_bf16_f32 v101, v70, v71
	v_cvt_pk_bf16_f32 v102, v72, v73
	v_cvt_pk_bf16_f32 v103, v74, v75
	s_waitcnt lgkmcnt(6)
	v_mfma_f32_32x32x16_bf16 v[34:49], v[80:83], v[138:141], v[34:49]
	ds_read_b64_tr_b16 v[138:139], v223 offset:0x2200
	ds_read_b64_tr_b16 v[140:141], v223 offset:0x2a00
	v_exp_f32_e32 v68, v108
	v_exp_f32_e32 v69, v109
	v_permlane32_swap_b32_e32 v100, v102
	v_permlane32_swap_b32_e32 v101, v103
	s_waitcnt lgkmcnt(6)
	v_mfma_f32_32x32x16_bf16 v[18:33], v[80:83], v[142:145], v[18:33]
	ds_read_b64_tr_b16 v[142:143], v223 offset:0x2400
	ds_read_b64_tr_b16 v[144:145], v223 offset:0x2c00
	v_exp_f32_e32 v70, v110
	v_exp_f32_e32 v71, v111
	v_exp_f32_e32 v72, v112
	s_waitcnt lgkmcnt(6)
	v_mfma_f32_32x32x16_bf16 v[2:17], v[80:83], v[198:201], v[2:17]
	ds_read_b64_tr_b16 v[198:199], v223 offset:0x2600
	ds_read_b64_tr_b16 v[200:201], v223 offset:0x2e00
	v_exp_f32_e32 v73, v113
	v_exp_f32_e32 v74, v114
	v_exp_f32_e32 v75, v115
	s_waitcnt lgkmcnt(6)
	v_mfma_f32_32x32x16_bf16 v[50:65], v[100:103], v[134:137], v[50:65]
	ds_read_b64_tr_b16 v[134:135], v223 offset:0x3000
	ds_read_b64_tr_b16 v[136:137], v223 offset:0x3800
	v_add_f32_e32 v0, v68, v0
	v_add_f32_e32 v0, v69, v0
	v_add_f32_e32 v0, v70, v0
	v_add_f32_e32 v0, v71, v0
	s_waitcnt lgkmcnt(6)
	v_mfma_f32_32x32x16_bf16 v[34:49], v[100:103], v[138:141], v[34:49]
	ds_read_b64_tr_b16 v[138:139], v223 offset:0x3200
	ds_read_b64_tr_b16 v[140:141], v223 offset:0x3a00
	v_add_f32_e32 v0, v72, v0
	v_add_f32_e32 v0, v73, v0
	v_add_f32_e32 v0, v74, v0
	v_add_f32_e32 v0, v75, v0
	v_mov_b32_e32 v231, v0
	s_waitcnt lgkmcnt(6)
	v_mfma_f32_32x32x16_bf16 v[18:33], v[100:103], v[142:145], v[18:33]
	ds_read_b64_tr_b16 v[142:143], v223 offset:0x3400
	ds_read_b64_tr_b16 v[144:145], v223 offset:0x3c00
	v_cvt_pk_bf16_f32 v104, v68, v69
	v_cvt_pk_bf16_f32 v105, v70, v71
	v_cvt_pk_bf16_f32 v106, v72, v73
	v_cvt_pk_bf16_f32 v107, v74, v75
	v_permlane32_swap_b32_e32 v0, v231
	s_waitcnt lgkmcnt(6)
	v_mfma_f32_32x32x16_bf16 v[2:17], v[100:103], v[198:201], v[2:17]
	ds_read_b64_tr_b16 v[198:199], v223 offset:0x3600
	ds_read_b64_tr_b16 v[200:201], v223 offset:0x3e00
	v_permlane32_swap_b32_e32 v104, v106
	v_permlane32_swap_b32_e32 v105, v107
	v_max_f32_e32 v132, v85, v85
	v_max_f32_e32 v133, v84, v84
	v_max_f32_e32 v132, v133, v132
	s_waitcnt lgkmcnt(6)
	v_mfma_f32_32x32x16_bf16 v[50:65], v[104:107], v[134:137], v[50:65]
	v_max3_f32 v132, v132, v86, v87
	v_max3_f32 v132, v132, v88, v89
	v_max3_f32 v132, v132, v90, v91
	v_max3_f32 v132, v132, v92, v93
	v_max3_f32 v132, v132, v94, v95
	s_waitcnt lgkmcnt(4)
	v_mfma_f32_32x32x16_bf16 v[34:49], v[104:107], v[138:141], v[34:49]
	v_max3_f32 v132, v132, v96, v97
	v_max3_f32 v132, v132, v98, v99
	v_max3_f32 v132, v132, v116, v117
	v_max3_f32 v132, v132, v118, v119
	v_max3_f32 v132, v132, v120, v121
	s_waitcnt lgkmcnt(2)
	v_mfma_f32_32x32x16_bf16 v[18:33], v[104:107], v[142:145], v[18:33]
	v_max3_f32 v132, v132, v122, v123
	v_max3_f32 v132, v132, v124, v125
	v_max3_f32 v132, v132, v126, v127
	v_max3_f32 v132, v132, v128, v129
	v_max3_f32 v132, v132, v130, v131
	v_mov_b32_e32 v133, v132
	s_waitcnt lgkmcnt(0)
	v_mfma_f32_32x32x16_bf16 v[2:17], v[104:107], v[198:201], v[2:17]
	v_permlane32_swap_b32_e32 v132, v133
	v_max_f32_e32 v133, v133, v133
	v_max_f32_e32 v132, v132, v132
	v_max_f32_e32 v100, v132, v133
	s_branch .Ljoin_h1
.Lcupd_f1:
	v_sub_f32_e32 v132, v133, v233
	v_mov_b32_e32 v66, v133
	v_mov_b32_e32 v236, v132
	v_mov_b32_e32 v237, v132
	v_mov_b32_e32 v238, v132
	v_mov_b32_e32 v239, v132
	v_mov_b32_e32 v240, v132
	v_mov_b32_e32 v241, v132
	v_mov_b32_e32 v242, v132
	v_mov_b32_e32 v243, v132
	v_mov_b32_e32 v244, v132
	v_mov_b32_e32 v245, v132
	v_mov_b32_e32 v246, v132
	v_mov_b32_e32 v247, v132
	v_mov_b32_e32 v248, v132
	v_mov_b32_e32 v249, v132
	v_mov_b32_e32 v250, v132
	v_mov_b32_e32 v251, v132
	s_nop 1
	s_branch .Lcret_f1

; #define SBAR() __builtin_amdgcn_sched_barrier(0)
; #define SLOAD(i, k0) do { sr_[i].vs0 = GLD8(&Vh[(long)((k0) + sr) * LD + sc]); sr_[i].vs1 = GLD8(&Vh[(long)((k0) + 32 + sr) * LD + sc]); \
;     if (DQK == 128) { sr_[i].ks0 = GLD8(&Kh[(long)((k0) + sr) * LD + sc]); sr_[i].ks1 = GLD8(&Kh[(long)((k0) + 32 + sr) * LD + sc]); } \
;     else { sr_[i].ks0 = GLD8(&Kh[(long)((k0) + kr) * LD + kc]); } } while (0)
; #define SWRITE(b, i) do { *(bf16x8*)(V_lds + (b) * SHM_V + vst0) = sr_[i].vs0; *(bf16x8*)(V_lds + (b) * SHM_V + vst1) = sr_[i].vs1; \
;     if (DQK == 128) { *(bf16x8*)(K_lds + (b) * SHM_K + KSWZ(sr, sc * 2)) = sr_[i].ks0; *(bf16x8*)(K_lds + (b) * SHM_K + KSWZ(32 + sr, sc * 2)) = sr_[i].ks1; } \
;     else { *(bf16x8*)(K_lds + (b) * SHM_K + KSWZ64(kr, kc * 2)) = sr_[i].ks0; } } while (0)
; template <int DQK, bool BIAS, bool VIRT = false>
; __device__ __forceinline__ void attn_pass(const bf16_t* __restrict__ Qb, const bf16_t* __restrict__ Kh, const bf16_t* __restrict__ Vh, int L, int NT, int qw0, const float* lut, f32x16 (&o)[4], char* lds, int nact) {
;     ...
;   SLOAD(SE, 0); asm volatile("s_waitcnt vmcnt(0)" ::: "memory"); SWRITE(0, SE); __syncthreads();
;   qkt<DQK>(pA0, pA1, K_lds, qr, r32, hi, negm); fixup<BIAS, VIRT>(pA0, pA1, 0, L, qw0, r32, hi, lut); partialSM<true>(pA0, pA1, m_reg, alA, negm, c_cur);
;   SLOAD(SO, KVBLK); if (SDEPTH == 2) { if (2 < NT) SLOAD(SE, 2 * KVBLK); }
;   SWAIT(); SWRITE(1, SO); __syncthreads();
;   for (int j = 1; j + 1 < NT; j += 2) {
;     NEGM(j); SBAR(); qkt<DQK>(pB0, pB1, K_lds + SHM_K, qr, r32, hi, negm);
;     finishSM(pA0, pA1, alA, l_reg, pa0, pa1, pa2, pa3); SBAR();
;     SLOAD(SO, (j + SDEPTH) * KVBLK); SBAR();
;     pv_d0(o, vb0, pa0, pa1, pa2, pa3); fixup<BIAS, VIRT>(pB0, pB1, j, L, qw0, r32, hi, lut); partialSM<false>(pB0, pB1, m_reg, alB, negm, c_cur);
;     __syncthreads(); SWAIT(); SWRITE(0, SE);
;     RESC(alB); __syncthreads();
;     NEGM(j + 1); SBAR(); qkt<DQK>(pA0, pA1, K_lds, qr, r32, hi, negm);
;     finishSM(pB0, pB1, alB, l_reg, pa0, pa1, pa2, pa3); SBAR();
;     if (SDEPTH == 1 || j + 3 < NT) SLOAD(SE, (j + 1 + SDEPTH) * KVBLK); SBAR();
;     pv_d0(o, vb0 + SHM_V, pa0, pa1, pa2, pa3); fixup<BIAS, VIRT>(pA0, pA1, j + 1, L, qw0, r32, hi, lut); partialSM<false>(pA0, pA1, m_reg, alA, negm, c_cur);
.LBB0_235:
	s_add_i32 s4, s25, -1
	s_add_i32 s99, s19, 0xffffffa1
	s_cmp_lt_u32 s99, 0xfffffea3
	s_cbranch_scc0 .Lold_h2
	s_add_i32 s99, s18, 64
	s_cmp_le_u32 s99, s47
	s_cbranch_scc0 .Lold_h2
	ds_read_b128 v[84:87], v225 offset:36864
	ds_read_b128 v[116:119], v225 offset:32768
	ds_read_b128 v[88:91], v227 offset:36864
	ds_read_b128 v[134:137], v227 offset:32768
	ds_read_b128 v[138:141], v228 offset:36864
	ds_read_b128 v[142:145], v228 offset:32768
	v_add_f32_e32 v235, 0, v219
	v_add_f32_e32 v235, v233, v235
	v_add_f32_e32 v235, v209, v235
	v_add_f32_e32 v235, v220, v235
	v_add_f32_e32 v235, v207, v235
	v_add_f32_e32 v235, v218, v235
	v_add_f32_e32 v235, v206, v235
	v_add_f32_e32 v235, v208, v235
	v_add_f32_e32 v235, v203, v235
	v_add_f32_e32 v235, v205, v235
	v_add_f32_e32 v235, v201, v235
	v_add_f32_e32 v235, v204, v235
	v_add_f32_e32 v235, v199, v235
	v_add_f32_e32 v235, v202, v235
	v_add_f32_e32 v235, v198, v235
	v_add_f32_e32 v235, v200, v235
	v_cvt_pk_bf16_f32 v92, v219, v233
	v_cvt_pk_bf16_f32 v93, v209, v220
	v_cvt_pk_bf16_f32 v94, v207, v218
	v_cvt_pk_bf16_f32 v95, v206, v208
	v_cvt_pk_bf16_f32 v96, v203, v205
	v_cvt_pk_bf16_f32 v97, v201, v204
	v_cvt_pk_bf16_f32 v98, v199, v202
	v_cvt_pk_bf16_f32 v99, v198, v200
	s_waitcnt lgkmcnt(6)
	v_cmp_neq_f32_e32 vcc, v133, v66
	s_cbranch_vccnz .Lcupd_f2
.Lcret_f2:
	s_waitcnt lgkmcnt(4)
	v_mfma_f32_32x32x16_bf16 v[68:83], v[116:119], v[162:165], v[236:251]
	v_mfma_f32_32x32x16_bf16 v[116:131], v[84:87], v[162:165], v[236:251]
	ds_read_b128 v[84:87], v226 offset:36864
	v_permlane32_swap_b32_e32 v92, v94
	v_permlane32_swap_b32_e32 v93, v95
	v_permlane32_swap_b32_e32 v96, v98
	v_permlane32_swap_b32_e32 v97, v99
	v_add_co_u32_e32 v132, vcc, 0x10341000, v148
	s_waitcnt lgkmcnt(3)
	v_mfma_f32_32x32x16_bf16 v[116:131], v[88:91], v[158:161], v[116:131]
	v_addc_co_u32_e32 v133, vcc, 0, v149, vcc
	v_add_co_u32_e32 v174, vcc, 0x10389000, v148
	v_mfma_f32_32x32x16_bf16 v[68:83], v[134:137], v[158:161], v[68:83]
	ds_read_b128 v[88:91], v226 offset:32768
	v_addc_co_u32_e32 v175, vcc, 0, v149, vcc
	v_add_co_u32_e32 v176, vcc, 0x10340000, v196
	s_waitcnt lgkmcnt(2)
	v_mfma_f32_32x32x16_bf16 v[116:131], v[138:141], v[154:157], v[116:131]
	v_addc_co_u32_e32 v177, vcc, 0, v197, vcc
	v_mfma_f32_32x32x16_bf16 v[68:83], v[142:145], v[154:157], v[68:83]
	ds_read_b64_tr_b16 v[134:135], v211 offset:0
	ds_read_b64_tr_b16 v[136:137], v211 offset:0x800
	ds_read_b64_tr_b16 v[138:139], v211 offset:0x200
	ds_read_b64_tr_b16 v[140:141], v211 offset:0xa00
	ds_read_b64_tr_b16 v[142:143], v211 offset:0x400
	ds_read_b64_tr_b16 v[144:145], v211 offset:0xc00
	ds_read_b64_tr_b16 v[146:147], v211 offset:0x600
	ds_read_b64_tr_b16 v[148:149], v211 offset:0xe00
	s_waitcnt lgkmcnt(8)
	v_mfma_f32_32x32x16_bf16 v[116:131], v[84:87], v[150:153], v[116:131]
	v_mfma_f32_32x32x16_bf16 v[68:83], v[88:91], v[150:153], v[68:83]
	s_cmp_ge_u32 s4, s28
	s_cbranch_scc1 .Lnold_h2
	global_load_dwordx4 v[166:169], v[132:133], off
	global_load_dwordx4 v[170:173], v[174:175], off
	global_load_dwordx4 v[174:177], v[176:177], off offset:2048
; #define SBAR() __builtin_amdgcn_sched_barrier(0)
; template <int D0> __device__ __forceinline__ void pv_one(f32x16& od, int vb, bf16x8 pa0, bf16x8 pa1, bf16x8 pa2, bf16x8 pa3) {
;   const s16x4 l0 = tr_read<v_rd_off(D0, 0, 0)>(vb), h0 = tr_read<v_rd_off(D0, 0, 1)>(vb), l1 = tr_read<v_rd_off(D0, 1, 0)>(vb), h1 = tr_read<v_rd_off(D0, 1, 1)>(vb);
;   const s16x4 l2 = tr_read<v_rd_off(D0, 2, 0)>(vb), h2 = tr_read<v_rd_off(D0, 2, 1)>(vb), l3 = tr_read<v_rd_off(D0, 3, 0)>(vb), h3 = tr_read<v_rd_off(D0, 3, 1)>(vb);
;   asm volatile("s_waitcnt lgkmcnt(0)" ::: "memory"); SBAR();
;     ...
;   od = __builtin_amdgcn_mfma_f32_32x32x16_bf16(pa0, PK(l0, h0), od, 0, 0, 0);
;   od = __builtin_amdgcn_mfma_f32_32x32x16_bf16(pa1, PK(l1, h1), od, 0, 0, 0);
;   od = __builtin_amdgcn_mfma_f32_32x32x16_bf16(pa2, PK(l2, h2), od, 0, 0, 0);
;   od = __builtin_amdgcn_mfma_f32_32x32x16_bf16(pa3, PK(l3, h3), od, 0, 0, 0);
;     ...
; }
; __device__ __forceinline__ void pv_d0(f32x16* o, int vb, bf16x8 pa0, bf16x8 pa1, bf16x8 pa2, bf16x8 pa3) {
;   pv_one<0>(o[0], vb, pa0, pa1, pa2, pa3); pv_one<1>(o[1], vb, pa0, pa1, pa2, pa3); pv_one<2>(o[2], vb, pa0, pa1, pa2, pa3); pv_one<3>(o[3], vb, pa0, pa1, pa2, pa3);
.Lnold_h2:
	s_addk_i32 s19, 0xffa1
	s_waitcnt lgkmcnt(6)
	v_mfma_f32_32x32x16_bf16 v[50:65], v[92:95], v[134:137], v[50:65]
	ds_read_b64_tr_b16 v[134:135], v211 offset:0x1000
	ds_read_b64_tr_b16 v[136:137], v211 offset:0x1800
	v_exp_f32_e32 v84, v100
	v_exp_f32_e32 v85, v101
	v_add_f32_e32 v235, v84, v235
	s_waitcnt lgkmcnt(6)
	v_mfma_f32_32x32x16_bf16 v[34:49], v[92:95], v[138:141], v[34:49]
	ds_read_b64_tr_b16 v[138:139], v211 offset:0x1200
	ds_read_b64_tr_b16 v[140:141], v211 offset:0x1a00
	v_exp_f32_e32 v86, v102
	v_add_f32_e32 v235, v85, v235
	v_exp_f32_e32 v87, v103
	v_add_f32_e32 v235, v86, v235
	s_waitcnt lgkmcnt(6)
	v_mfma_f32_32x32x16_bf16 v[18:33], v[92:95], v[142:145], v[18:33]
	ds_read_b64_tr_b16 v[142:143], v211 offset:0x1400
	ds_read_b64_tr_b16 v[144:145], v211 offset:0x1c00
	v_exp_f32_e32 v88, v104
	v_add_f32_e32 v235, v87, v235
	v_exp_f32_e32 v89, v105
	v_add_f32_e32 v235, v88, v235
	s_waitcnt lgkmcnt(6)
	v_mfma_f32_32x32x16_bf16 v[2:17], v[92:95], v[146:149], v[2:17]
	ds_read_b64_tr_b16 v[146:147], v211 offset:0x1600
	ds_read_b64_tr_b16 v[148:149], v211 offset:0x1e00
	v_exp_f32_e32 v90, v106
	v_add_f32_e32 v235, v89, v235
	v_exp_f32_e32 v91, v107
	v_add_f32_e32 v235, v90, v235
	v_add_f32_e32 v235, v91, v235
	s_waitcnt lgkmcnt(6)
	v_mfma_f32_32x32x16_bf16 v[50:65], v[96:99], v[134:137], v[50:65]
	ds_read_b64_tr_b16 v[134:135], v211 offset:0x2000
	ds_read_b64_tr_b16 v[136:137], v211 offset:0x2800
	v_cvt_pk_bf16_f32 v100, v84, v85
	v_cvt_pk_bf16_f32 v101, v86, v87
	v_cvt_pk_bf16_f32 v102, v88, v89
	v_cvt_pk_bf16_f32 v103, v90, v91
	s_waitcnt lgkmcnt(6)
	v_mfma_f32_32x32x16_bf16 v[34:49], v[96:99], v[138:141], v[34:49]
	ds_read_b64_tr_b16 v[138:139], v211 offset:0x2200
	ds_read_b64_tr_b16 v[140:141], v211 offset:0x2a00
	v_exp_f32_e32 v84, v108
	v_exp_f32_e32 v85, v109
	v_permlane32_swap_b32_e32 v100, v102
	v_permlane32_swap_b32_e32 v101, v103
	s_waitcnt lgkmcnt(6)
	v_mfma_f32_32x32x16_bf16 v[18:33], v[96:99], v[142:145], v[18:33]
	ds_read_b64_tr_b16 v[142:143], v211 offset:0x2400
	ds_read_b64_tr_b16 v[144:145], v211 offset:0x2c00
	v_exp_f32_e32 v86, v110
	v_exp_f32_e32 v87, v111
	v_exp_f32_e32 v88, v112
	s_waitcnt lgkmcnt(6)
	v_mfma_f32_32x32x16_bf16 v[2:17], v[96:99], v[146:149], v[2:17]
	ds_read_b64_tr_b16 v[146:147], v211 offset:0x2600
	ds_read_b64_tr_b16 v[148:149], v211 offset:0x2e00
	v_exp_f32_e32 v89, v113
	v_exp_f32_e32 v90, v114
	v_exp_f32_e32 v91, v115
	s_waitcnt lgkmcnt(6)
	v_mfma_f32_32x32x16_bf16 v[50:65], v[100:103], v[134:137], v[50:65]
	ds_read_b64_tr_b16 v[134:135], v211 offset:0x3000
	ds_read_b64_tr_b16 v[136:137], v211 offset:0x3800
	v_add_f32_e32 v235, v84, v235
	v_add_f32_e32 v235, v85, v235
	v_add_f32_e32 v235, v86, v235
	v_add_f32_e32 v235, v87, v235
	s_waitcnt lgkmcnt(6)
	v_mfma_f32_32x32x16_bf16 v[34:49], v[100:103], v[138:141], v[34:49]
	ds_read_b64_tr_b16 v[138:139], v211 offset:0x3200
	ds_read_b64_tr_b16 v[140:141], v211 offset:0x3a00
	v_add_f32_e32 v235, v88, v235
	v_add_f32_e32 v235, v89, v235
	v_add_f32_e32 v235, v90, v235
	v_add_f32_e32 v235, v91, v235
	v_mov_b32_e32 v252, v235
	s_waitcnt lgkmcnt(6)
	v_mfma_f32_32x32x16_bf16 v[18:33], v[100:103], v[142:145], v[18:33]
	ds_read_b64_tr_b16 v[142:143], v211 offset:0x3400
	ds_read_b64_tr_b16 v[144:145], v211 offset:0x3c00
	v_cvt_pk_bf16_f32 v104, v84, v85
	v_cvt_pk_bf16_f32 v105, v86, v87
	v_cvt_pk_bf16_f32 v106, v88, v89
	v_cvt_pk_bf16_f32 v107, v90, v91
	v_permlane32_swap_b32_e32 v235, v252
	s_waitcnt lgkmcnt(6)
	v_mfma_f32_32x32x16_bf16 v[2:17], v[100:103], v[146:149], v[2:17]
	ds_read_b64_tr_b16 v[146:147], v211 offset:0x3600
	ds_read_b64_tr_b16 v[148:149], v211 offset:0x3e00
	v_permlane32_swap_b32_e32 v104, v106
	v_permlane32_swap_b32_e32 v105, v107
	v_max_f32_e32 v132, v69, v69
	v_max_f32_e32 v133, v68, v68
	v_max_f32_e32 v132, v133, v132
	s_waitcnt lgkmcnt(6)
	v_mfma_f32_32x32x16_bf16 v[50:65], v[104:107], v[134:137], v[50:65]
	v_max3_f32 v132, v132, v70, v71
	v_max3_f32 v132, v132, v72, v73
	v_max3_f32 v132, v132, v74, v75
	v_max3_f32 v132, v132, v76, v77
	v_max3_f32 v132, v132, v78, v79
	s_waitcnt lgkmcnt(4)
	v_mfma_f32_32x32x16_bf16 v[34:49], v[104:107], v[138:141], v[34:49]
	v_max3_f32 v132, v132, v80, v81
	v_max3_f32 v132, v132, v82, v83
	v_max3_f32 v132, v132, v116, v117
	v_max3_f32 v132, v132, v118, v119
	v_max3_f32 v132, v132, v120, v121
	s_waitcnt lgkmcnt(2)
	v_mfma_f32_32x32x16_bf16 v[18:33], v[104:107], v[142:145], v[18:33]
	v_max3_f32 v132, v132, v122, v123
	v_max3_f32 v132, v132, v124, v125
	v_max3_f32 v132, v132, v126, v127
	v_max3_f32 v132, v132, v128, v129
	v_max3_f32 v132, v132, v130, v131
	v_mov_b32_e32 v133, v132
	s_waitcnt lgkmcnt(0)
	v_mfma_f32_32x32x16_bf16 v[2:17], v[104:107], v[146:149], v[2:17]
	v_permlane32_swap_b32_e32 v132, v133
	v_max_f32_e32 v133, v133, v133
	v_max_f32_e32 v132, v132, v132
	v_max_f32_e32 v196, v132, v133
	s_branch .Ljoin_h2
.Lcupd_f2:
	v_sub_f32_e32 v132, v133, v234
	v_mov_b32_e32 v66, v133
	v_mov_b32_e32 v236, v132
	v_mov_b32_e32 v237, v132
	v_mov_b32_e32 v238, v132
	v_mov_b32_e32 v239, v132
	v_mov_b32_e32 v240, v132
	v_mov_b32_e32 v241, v132
	v_mov_b32_e32 v242, v132
	v_mov_b32_e32 v243, v132
	v_mov_b32_e32 v244, v132
	v_mov_b32_e32 v245, v132
	v_mov_b32_e32 v246, v132
	v_mov_b32_e32 v247, v132
	v_mov_b32_e32 v248, v132
	v_mov_b32_e32 v249, v132
	v_mov_b32_e32 v250, v132
	v_mov_b32_e32 v251, v132
	s_nop 1
	s_branch .Lcret_f2
